# grid barrier: the first workgroup of each XCD to arrive also starts an L2 write-back, so the leader's final write-back has less left
# speedup vs baseline: 1.0041x; 1.0041x over previous
.LBB0_112:
	s_or_b64 exec, exec, s[10:11]
	v_cvt_f32_u32_e32 v4, v2
	s_waitcnt vmcnt(0)
	v_readfirstlane_b32 s3, v3
	v_sub_u32_e32 v3, 0, v2
	v_rcp_iflag_f32_e32 v4, v4
	v_add_u32_e32 v5, s3, v1
	v_mul_f32_e32 v4, 0x4f7ffffe, v4
	v_cvt_u32_f32_e32 v4, v4
	v_mul_lo_u32 v1, v3, v4
	v_mul_hi_u32 v1, v4, v1
	v_add_u32_e32 v1, v4, v1
	v_mul_hi_u32 v1, v5, v1
	v_mul_lo_u32 v3, v1, v2
	v_sub_u32_e32 v3, v5, v3
	v_add_u32_e32 v4, 1, v1
	v_cmp_ge_u32_e32 vcc, v3, v2
	s_nop 1
	v_cndmask_b32_e32 v1, v1, v4, vcc
	v_sub_u32_e32 v4, v3, v2
	v_cndmask_b32_e32 v3, v3, v4, vcc
	v_add_u32_e32 v4, 1, v1
	v_cmp_ge_u32_e32 vcc, v3, v2
	v_add_u32_e32 v3, 1, v5
	s_nop 0
	v_cndmask_b32_e32 v1, v1, v4, vcc
	v_mul_lo_u32 v4, v2, v1
	v_add_u32_e32 v2, v4, v2
	v_cmp_ne_u32_e32 vcc, v3, v2
	s_waitcnt lgkmcnt(0)
	v_add_u32_e32 v1, 1, v1
	v_mul_lo_u32 v1, v1, v0
	s_cbranch_vccnz .Lgb1_early
	buffer_wbl2 sc1
	s_waitcnt vmcnt(0)
	v_mov_b32_e32 v2, 0x3000
	v_mov_b32_e32 v3, 1
	global_atomic_add v2, v3, s[48:49] offset:1024
	s_branch .Lgb1_poll
.Lgb1_early:
	v_cmp_ne_u32_e32 vcc, v5, v4
	s_cbranch_vccnz .Lgb1_poll
	buffer_wbl2 sc1

.LBB0_1477:
	s_or_b64 exec, exec, s[6:7]
	v_cvt_f32_u32_e32 v4, v2
	s_waitcnt vmcnt(0)
	v_readfirstlane_b32 s4, v3
	v_sub_u32_e32 v3, 0, v2
	v_rcp_iflag_f32_e32 v4, v4
	v_add_u32_e32 v5, s4, v1
	v_mul_f32_e32 v4, 0x4f7ffffe, v4
	v_cvt_u32_f32_e32 v4, v4
	v_mul_lo_u32 v1, v3, v4
	v_mul_hi_u32 v1, v4, v1
	v_add_u32_e32 v1, v4, v1
	v_mul_hi_u32 v1, v5, v1
	v_mul_lo_u32 v3, v1, v2
	v_sub_u32_e32 v3, v5, v3
	v_add_u32_e32 v4, 1, v1
	v_cmp_ge_u32_e32 vcc, v3, v2
	s_nop 1
	v_cndmask_b32_e32 v1, v1, v4, vcc
	v_sub_u32_e32 v4, v3, v2
	v_cndmask_b32_e32 v3, v3, v4, vcc
	v_add_u32_e32 v4, 1, v1
	v_cmp_ge_u32_e32 vcc, v3, v2
	v_add_u32_e32 v3, 1, v5
	s_nop 0
	v_cndmask_b32_e32 v1, v1, v4, vcc
	v_mul_lo_u32 v4, v2, v1
	v_add_u32_e32 v2, v4, v2
	v_cmp_ne_u32_e32 vcc, v3, v2
	s_waitcnt lgkmcnt(0)
	v_add_u32_e32 v1, 1, v1
	v_mul_lo_u32 v1, v1, v0
	s_cbranch_vccnz .Lgb17_early
	buffer_wbl2 sc1
	s_waitcnt vmcnt(0)
	v_mov_b32_e32 v2, 0x3000
	v_mov_b32_e32 v3, 1
	global_atomic_add v2, v3, s[48:49] offset:1024
	s_branch .Lgb17_poll
